# P7 SwiGLU epilogue hand-rewritten: packed f32 mul/add pairs (same IEEE ops per element), addresses formed once
# baseline (speedup 1.0000x reference)
.LBB0_884:
	v_lshl_add_u32 v150, s16, 8, v144
	v_lshl_or_b32 v152, s39, 7, v146
	v_mov_b32_e32 v153, 0
	v_mov_b64_e32 v[154:155], s[48:49]
	v_mad_i64_i32 v[154:155], s[18:19], v150, s38, v[154:155]
	s_mov_b32 s40, 0x16000
	s_mov_b32 s41, 0
	s_mov_b32 s42, 0x6e000
	s_mov_b32 s43, 0
	s_mov_b32 s44, 0xbfb8aa3b
	s_mov_b32 s45, 0xbfb8aa3b
	v_lshl_add_u64 v[156:157], v[152:153], 1, v[154:155]
	v_pk_mul_f32 v[200:201], v[124:125], s[44:45]
	v_pk_mul_f32 v[202:203], v[126:127], s[44:45]
	v_pk_mul_f32 v[204:205], v[120:121], s[44:45]
	v_pk_mul_f32 v[206:207], v[122:123], s[44:45]
	v_exp_f32_e32 v200, v200
	v_exp_f32_e32 v201, v201
	v_exp_f32_e32 v202, v202
	v_exp_f32_e32 v203, v203
	v_exp_f32_e32 v204, v204
	v_exp_f32_e32 v205, v205
	v_exp_f32_e32 v206, v206
	v_exp_f32_e32 v207, v207
	v_pk_add_f32 v[200:201], v[200:201], 1.0 op_sel_hi:[1,0]
	v_pk_add_f32 v[202:203], v[202:203], 1.0 op_sel_hi:[1,0]
	v_pk_add_f32 v[204:205], v[204:205], 1.0 op_sel_hi:[1,0]
	v_pk_add_f32 v[206:207], v[206:207], 1.0 op_sel_hi:[1,0]
	v_rcp_f32_e32 v200, v200
	v_rcp_f32_e32 v201, v201
	v_rcp_f32_e32 v202, v202
	v_rcp_f32_e32 v203, v203
	v_rcp_f32_e32 v204, v204
	v_rcp_f32_e32 v205, v205
	v_rcp_f32_e32 v206, v206
	v_rcp_f32_e32 v207, v207
	v_pk_mul_f32 v[200:201], v[124:125], v[200:201]
	v_pk_mul_f32 v[202:203], v[126:127], v[202:203]
	v_pk_mul_f32 v[204:205], v[120:121], v[204:205]
	v_pk_mul_f32 v[206:207], v[122:123], v[206:207]
	v_pk_mul_f32 v[116:117], v[200:201], v[116:117]
	v_pk_mul_f32 v[118:119], v[202:203], v[118:119]
	v_pk_mul_f32 v[112:113], v[204:205], v[112:113]
	v_pk_mul_f32 v[114:115], v[206:207], v[114:115]
	v_cvt_pk_bf16_f32 v116, v116, v117
	v_cvt_pk_bf16_f32 v117, v118, v119
	v_cvt_pk_bf16_f32 v118, v112, v113
	v_cvt_pk_bf16_f32 v119, v114, v115
	global_store_dwordx4 v[156:157], v[116:119], off
	v_lshl_add_u64 v[156:157], v[156:157], 0, s[40:41]
	v_pk_mul_f32 v[200:201], v[108:109], s[44:45]
	v_pk_mul_f32 v[202:203], v[110:111], s[44:45]
	v_pk_mul_f32 v[204:205], v[104:105], s[44:45]
	v_pk_mul_f32 v[206:207], v[106:107], s[44:45]
	v_exp_f32_e32 v200, v200
	v_exp_f32_e32 v201, v201
	v_exp_f32_e32 v202, v202
	v_exp_f32_e32 v203, v203
	v_exp_f32_e32 v204, v204
	v_exp_f32_e32 v205, v205
	v_exp_f32_e32 v206, v206
	v_exp_f32_e32 v207, v207
	v_pk_add_f32 v[200:201], v[200:201], 1.0 op_sel_hi:[1,0]
	v_pk_add_f32 v[202:203], v[202:203], 1.0 op_sel_hi:[1,0]
	v_pk_add_f32 v[204:205], v[204:205], 1.0 op_sel_hi:[1,0]
	v_pk_add_f32 v[206:207], v[206:207], 1.0 op_sel_hi:[1,0]
	v_rcp_f32_e32 v200, v200
	v_rcp_f32_e32 v201, v201
	v_rcp_f32_e32 v202, v202
	v_rcp_f32_e32 v203, v203
	v_rcp_f32_e32 v204, v204
	v_rcp_f32_e32 v205, v205
	v_rcp_f32_e32 v206, v206
	v_rcp_f32_e32 v207, v207
	v_pk_mul_f32 v[200:201], v[108:109], v[200:201]
	v_pk_mul_f32 v[202:203], v[110:111], v[202:203]
	v_pk_mul_f32 v[204:205], v[104:105], v[204:205]
	v_pk_mul_f32 v[206:207], v[106:107], v[206:207]
	v_pk_mul_f32 v[100:101], v[200:201], v[100:101]
	v_pk_mul_f32 v[102:103], v[202:203], v[102:103]
	v_pk_mul_f32 v[96:97], v[204:205], v[96:97]
	v_pk_mul_f32 v[98:99], v[206:207], v[98:99]
	v_cvt_pk_bf16_f32 v100, v100, v101
	v_cvt_pk_bf16_f32 v101, v102, v103
	v_cvt_pk_bf16_f32 v102, v96, v97
	v_cvt_pk_bf16_f32 v103, v98, v99
	global_store_dwordx4 v[156:157], v[100:103], off
	v_lshl_add_u64 v[156:157], v[156:157], 0, s[40:41]
	v_pk_mul_f32 v[200:201], v[92:93], s[44:45]
	v_pk_mul_f32 v[202:203], v[94:95], s[44:45]
	v_pk_mul_f32 v[204:205], v[88:89], s[44:45]
	v_pk_mul_f32 v[206:207], v[90:91], s[44:45]
	v_exp_f32_e32 v200, v200
	v_exp_f32_e32 v201, v201
	v_exp_f32_e32 v202, v202
	v_exp_f32_e32 v203, v203
	v_exp_f32_e32 v204, v204
	v_exp_f32_e32 v205, v205
	v_exp_f32_e32 v206, v206
	v_exp_f32_e32 v207, v207
	v_pk_add_f32 v[200:201], v[200:201], 1.0 op_sel_hi:[1,0]
	v_pk_add_f32 v[202:203], v[202:203], 1.0 op_sel_hi:[1,0]
	v_pk_add_f32 v[204:205], v[204:205], 1.0 op_sel_hi:[1,0]
	v_pk_add_f32 v[206:207], v[206:207], 1.0 op_sel_hi:[1,0]
	v_rcp_f32_e32 v200, v200
	v_rcp_f32_e32 v201, v201
	v_rcp_f32_e32 v202, v202
	v_rcp_f32_e32 v203, v203
	v_rcp_f32_e32 v204, v204
	v_rcp_f32_e32 v205, v205
	v_rcp_f32_e32 v206, v206
	v_rcp_f32_e32 v207, v207
	v_pk_mul_f32 v[200:201], v[92:93], v[200:201]
	v_pk_mul_f32 v[202:203], v[94:95], v[202:203]
	v_pk_mul_f32 v[204:205], v[88:89], v[204:205]
	v_pk_mul_f32 v[206:207], v[90:91], v[206:207]
	v_pk_mul_f32 v[84:85], v[200:201], v[84:85]
	v_pk_mul_f32 v[86:87], v[202:203], v[86:87]
	v_pk_mul_f32 v[80:81], v[204:205], v[80:81]
	v_pk_mul_f32 v[82:83], v[206:207], v[82:83]
	v_cvt_pk_bf16_f32 v84, v84, v85
	v_cvt_pk_bf16_f32 v85, v86, v87
	v_cvt_pk_bf16_f32 v86, v80, v81
	v_cvt_pk_bf16_f32 v87, v82, v83
	global_store_dwordx4 v[156:157], v[84:87], off
	v_lshl_add_u64 v[156:157], v[156:157], 0, s[40:41]
	v_pk_mul_f32 v[200:201], v[76:77], s[44:45]
	v_pk_mul_f32 v[202:203], v[78:79], s[44:45]
	v_pk_mul_f32 v[204:205], v[72:73], s[44:45]
	v_pk_mul_f32 v[206:207], v[74:75], s[44:45]
	v_exp_f32_e32 v200, v200
	v_exp_f32_e32 v201, v201
	v_exp_f32_e32 v202, v202
	v_exp_f32_e32 v203, v203
	v_exp_f32_e32 v204, v204
	v_exp_f32_e32 v205, v205
	v_exp_f32_e32 v206, v206
	v_exp_f32_e32 v207, v207
	v_pk_add_f32 v[200:201], v[200:201], 1.0 op_sel_hi:[1,0]
	v_pk_add_f32 v[202:203], v[202:203], 1.0 op_sel_hi:[1,0]
	v_pk_add_f32 v[204:205], v[204:205], 1.0 op_sel_hi:[1,0]
	v_pk_add_f32 v[206:207], v[206:207], 1.0 op_sel_hi:[1,0]
	v_rcp_f32_e32 v200, v200
	v_rcp_f32_e32 v201, v201
	v_rcp_f32_e32 v202, v202
	v_rcp_f32_e32 v203, v203
	v_rcp_f32_e32 v204, v204
	v_rcp_f32_e32 v205, v205
	v_rcp_f32_e32 v206, v206
	v_rcp_f32_e32 v207, v207
	v_pk_mul_f32 v[200:201], v[76:77], v[200:201]
	v_pk_mul_f32 v[202:203], v[78:79], v[202:203]
	v_pk_mul_f32 v[204:205], v[72:73], v[204:205]
	v_pk_mul_f32 v[206:207], v[74:75], v[206:207]
	v_pk_mul_f32 v[68:69], v[200:201], v[68:69]
	v_pk_mul_f32 v[70:71], v[202:203], v[70:71]
	v_pk_mul_f32 v[64:65], v[204:205], v[64:65]
	v_pk_mul_f32 v[66:67], v[206:207], v[66:67]
	v_cvt_pk_bf16_f32 v68, v68, v69
	v_cvt_pk_bf16_f32 v69, v70, v71
	v_cvt_pk_bf16_f32 v70, v64, v65
	v_cvt_pk_bf16_f32 v71, v66, v67
	global_store_dwordx4 v[156:157], v[68:71], off
	v_lshl_add_u64 v[156:157], v[156:157], 0, s[42:43]
	v_pk_mul_f32 v[200:201], v[60:61], s[44:45]
	v_pk_mul_f32 v[202:203], v[62:63], s[44:45]
	v_pk_mul_f32 v[204:205], v[56:57], s[44:45]
	v_pk_mul_f32 v[206:207], v[58:59], s[44:45]
	v_exp_f32_e32 v200, v200
	v_exp_f32_e32 v201, v201
	v_exp_f32_e32 v202, v202
	v_exp_f32_e32 v203, v203
	v_exp_f32_e32 v204, v204
	v_exp_f32_e32 v205, v205
	v_exp_f32_e32 v206, v206
	v_exp_f32_e32 v207, v207
	v_pk_add_f32 v[200:201], v[200:201], 1.0 op_sel_hi:[1,0]
	v_pk_add_f32 v[202:203], v[202:203], 1.0 op_sel_hi:[1,0]
	v_pk_add_f32 v[204:205], v[204:205], 1.0 op_sel_hi:[1,0]
	v_pk_add_f32 v[206:207], v[206:207], 1.0 op_sel_hi:[1,0]
	v_rcp_f32_e32 v200, v200
	v_rcp_f32_e32 v201, v201
	v_rcp_f32_e32 v202, v202
	v_rcp_f32_e32 v203, v203
	v_rcp_f32_e32 v204, v204
	v_rcp_f32_e32 v205, v205
	v_rcp_f32_e32 v206, v206
	v_rcp_f32_e32 v207, v207
	v_pk_mul_f32 v[200:201], v[60:61], v[200:201]
	v_pk_mul_f32 v[202:203], v[62:63], v[202:203]
	v_pk_mul_f32 v[204:205], v[56:57], v[204:205]
	v_pk_mul_f32 v[206:207], v[58:59], v[206:207]
	v_pk_mul_f32 v[52:53], v[200:201], v[52:53]
	v_pk_mul_f32 v[54:55], v[202:203], v[54:55]
	v_pk_mul_f32 v[48:49], v[204:205], v[48:49]
	v_pk_mul_f32 v[50:51], v[206:207], v[50:51]
	v_cvt_pk_bf16_f32 v52, v52, v53
	v_cvt_pk_bf16_f32 v53, v54, v55
	v_cvt_pk_bf16_f32 v54, v48, v49
	v_cvt_pk_bf16_f32 v55, v50, v51
	global_store_dwordx4 v[156:157], v[52:55], off
	v_lshl_add_u64 v[156:157], v[156:157], 0, s[40:41]
	v_pk_mul_f32 v[200:201], v[44:45], s[44:45]
	v_pk_mul_f32 v[202:203], v[46:47], s[44:45]
	v_pk_mul_f32 v[204:205], v[40:41], s[44:45]
	v_pk_mul_f32 v[206:207], v[42:43], s[44:45]
	v_exp_f32_e32 v200, v200
	v_exp_f32_e32 v201, v201
	v_exp_f32_e32 v202, v202
	v_exp_f32_e32 v203, v203
	v_exp_f32_e32 v204, v204
	v_exp_f32_e32 v205, v205
	v_exp_f32_e32 v206, v206
	v_exp_f32_e32 v207, v207
	v_pk_add_f32 v[200:201], v[200:201], 1.0 op_sel_hi:[1,0]
	v_pk_add_f32 v[202:203], v[202:203], 1.0 op_sel_hi:[1,0]
	v_pk_add_f32 v[204:205], v[204:205], 1.0 op_sel_hi:[1,0]
	v_pk_add_f32 v[206:207], v[206:207], 1.0 op_sel_hi:[1,0]
	v_rcp_f32_e32 v200, v200
	v_rcp_f32_e32 v201, v201
	v_rcp_f32_e32 v202, v202
	v_rcp_f32_e32 v203, v203
	v_rcp_f32_e32 v204, v204
	v_rcp_f32_e32 v205, v205
	v_rcp_f32_e32 v206, v206
	v_rcp_f32_e32 v207, v207
	v_pk_mul_f32 v[200:201], v[44:45], v[200:201]
	v_pk_mul_f32 v[202:203], v[46:47], v[202:203]
	v_pk_mul_f32 v[204:205], v[40:41], v[204:205]
	v_pk_mul_f32 v[206:207], v[42:43], v[206:207]
	v_pk_mul_f32 v[36:37], v[200:201], v[36:37]
	v_pk_mul_f32 v[38:39], v[202:203], v[38:39]
	v_pk_mul_f32 v[32:33], v[204:205], v[32:33]
	v_pk_mul_f32 v[34:35], v[206:207], v[34:35]
	v_cvt_pk_bf16_f32 v36, v36, v37
	v_cvt_pk_bf16_f32 v37, v38, v39
	v_cvt_pk_bf16_f32 v38, v32, v33
	v_cvt_pk_bf16_f32 v39, v34, v35
	global_store_dwordx4 v[156:157], v[36:39], off
	v_lshl_add_u64 v[156:157], v[156:157], 0, s[40:41]
	v_pk_mul_f32 v[200:201], v[28:29], s[44:45]
	v_pk_mul_f32 v[202:203], v[30:31], s[44:45]
	v_pk_mul_f32 v[204:205], v[24:25], s[44:45]
	v_pk_mul_f32 v[206:207], v[26:27], s[44:45]
	v_exp_f32_e32 v200, v200
	v_exp_f32_e32 v201, v201
	v_exp_f32_e32 v202, v202
	v_exp_f32_e32 v203, v203
	v_exp_f32_e32 v204, v204
	v_exp_f32_e32 v205, v205
	v_exp_f32_e32 v206, v206
	v_exp_f32_e32 v207, v207
	v_pk_add_f32 v[200:201], v[200:201], 1.0 op_sel_hi:[1,0]
	v_pk_add_f32 v[202:203], v[202:203], 1.0 op_sel_hi:[1,0]
	v_pk_add_f32 v[204:205], v[204:205], 1.0 op_sel_hi:[1,0]
	v_pk_add_f32 v[206:207], v[206:207], 1.0 op_sel_hi:[1,0]
	v_rcp_f32_e32 v200, v200
	v_rcp_f32_e32 v201, v201
	v_rcp_f32_e32 v202, v202
	v_rcp_f32_e32 v203, v203
	v_rcp_f32_e32 v204, v204
	v_rcp_f32_e32 v205, v205
	v_rcp_f32_e32 v206, v206
	v_rcp_f32_e32 v207, v207
	v_pk_mul_f32 v[200:201], v[28:29], v[200:201]
	v_pk_mul_f32 v[202:203], v[30:31], v[202:203]
	v_pk_mul_f32 v[204:205], v[24:25], v[204:205]
	v_pk_mul_f32 v[206:207], v[26:27], v[206:207]
	v_pk_mul_f32 v[20:21], v[200:201], v[20:21]
	v_pk_mul_f32 v[22:23], v[202:203], v[22:23]
	v_pk_mul_f32 v[16:17], v[204:205], v[16:17]
	v_pk_mul_f32 v[18:19], v[206:207], v[18:19]
	v_cvt_pk_bf16_f32 v20, v20, v21
	v_cvt_pk_bf16_f32 v21, v22, v23
	v_cvt_pk_bf16_f32 v22, v16, v17
	v_cvt_pk_bf16_f32 v23, v18, v19
	global_store_dwordx4 v[156:157], v[20:23], off
	v_lshl_add_u64 v[156:157], v[156:157], 0, s[40:41]
	v_pk_mul_f32 v[200:201], v[12:13], s[44:45]
	v_pk_mul_f32 v[202:203], v[14:15], s[44:45]
	v_pk_mul_f32 v[204:205], v[8:9], s[44:45]
	v_pk_mul_f32 v[206:207], v[10:11], s[44:45]
	v_exp_f32_e32 v200, v200
	v_exp_f32_e32 v201, v201
	v_exp_f32_e32 v202, v202
	v_exp_f32_e32 v203, v203
	v_exp_f32_e32 v204, v204
	v_exp_f32_e32 v205, v205
	v_exp_f32_e32 v206, v206
	v_exp_f32_e32 v207, v207
	v_pk_add_f32 v[200:201], v[200:201], 1.0 op_sel_hi:[1,0]
	v_pk_add_f32 v[202:203], v[202:203], 1.0 op_sel_hi:[1,0]
	v_pk_add_f32 v[204:205], v[204:205], 1.0 op_sel_hi:[1,0]
	v_pk_add_f32 v[206:207], v[206:207], 1.0 op_sel_hi:[1,0]
	v_rcp_f32_e32 v200, v200
	v_rcp_f32_e32 v201, v201
	v_rcp_f32_e32 v202, v202
	v_rcp_f32_e32 v203, v203
	v_rcp_f32_e32 v204, v204
	v_rcp_f32_e32 v205, v205
	v_rcp_f32_e32 v206, v206
	v_rcp_f32_e32 v207, v207
	v_pk_mul_f32 v[200:201], v[12:13], v[200:201]
	v_pk_mul_f32 v[202:203], v[14:15], v[202:203]
	v_pk_mul_f32 v[204:205], v[8:9], v[204:205]
	v_pk_mul_f32 v[206:207], v[10:11], v[206:207]
	v_pk_mul_f32 v[4:5], v[200:201], v[4:5]
	v_pk_mul_f32 v[6:7], v[202:203], v[6:7]
	v_pk_mul_f32 v[0:1], v[204:205], v[0:1]
	v_pk_mul_f32 v[2:3], v[206:207], v[2:3]
	v_cvt_pk_bf16_f32 v4, v4, v5
	v_cvt_pk_bf16_f32 v5, v6, v7
	v_cvt_pk_bf16_f32 v6, v0, v1
	v_cvt_pk_bf16_f32 v7, v2, v3
	global_store_dwordx4 v[156:157], v[4:7], off
	s_andn2_b64 vcc, exec, s[2:3]
	s_mov_b64 s[2:3], -1
	s_cbranch_vccnz .LBB0_877
	s_andn2_b64 vcc, exec, s[0:1]
	s_cbranch_vccnz .LBB0_876
	s_barrier
	s_branch .LBB0_876
